# dsa_select sweeps hand-scheduled; head-weighted relu sum moved to a second f16 MFMA; winners deferred per chunk; floor sampling removed
# speedup vs baseline: 1.0301x; 1.0301x over previous
; template <int PASS> ...
;     const int sw = (fr >> 1) & 7;
;     const unsigned char* lp = buf + fr * 128;
; #pragma unroll
;     for (int hb = 0; hb < 2; ++hb) {
;         h16x8 kf[8][2];
; #pragma unroll
;         for (int e = 0; e < 8; ++e) { const unsigned char* tp = lp + (hb * 8 + e) * 2048; kf[e][0] = *(const h16x8*)(tp + ((fq ^ sw) << 4)); kf[e][1] = *(const h16x8*)(tp + (((fq + 4) ^ sw) << 4)); }
; #pragma unroll
;         for (int e = 0; e < 8; ++e) { const int T = Tbase + hb * 8 + e;
;             f32x4 a0 = (f32x4){0.f, 0.f, 0.f, 0.f}, a1 = a0;
;             a0 = __builtin_amdgcn_mfma_f32_16x16x32_f16(aq[0][0], kf[e][0], a0, 0, 0, 0); a0 = __builtin_amdgcn_mfma_f32_16x16x32_f16(aq[0][1], kf[e][1], a0, 0, 0, 0);
;             a1 = __builtin_amdgcn_mfma_f32_16x16x32_f16(aq[1][0], kf[e][0], a1, 0, 0, 0); a1 = __builtin_amdgcn_mfma_f32_16x16x32_f16(aq[1][1], kf[e][1], a1, 0, 0, 0);
;             const h16x2 z2 = (h16x2){(h16)0.f, (h16)0.f};
;             const h16x2 r0 = __builtin_elementwise_max(__builtin_bit_cast(h16x2, __builtin_amdgcn_cvt_pkrtz(a0[0], a0[1])), z2), r1 = __builtin_elementwise_max(__builtin_bit_cast(h16x2, __builtin_amdgcn_cvt_pkrtz(a0[2], a0[3])), z2);
;             const h16x2 r2 = __builtin_elementwise_max(__builtin_bit_cast(h16x2, __builtin_amdgcn_cvt_pkrtz(a1[0], a1[1])), z2), r3 = __builtin_elementwise_max(__builtin_bit_cast(h16x2, __builtin_amdgcn_cvt_pkrtz(a1[2], a1[3])), z2);
;             const float sa = __builtin_amdgcn_fdot2(r0, wp[0], __builtin_amdgcn_fdot2(r1, wp[1], __builtin_amdgcn_fdot2(r2, wp[2], __builtin_amdgcn_fdot2(r3, wp[3], 0.f, false), false), false), false);
;             const int key = 16 * T + fr;
;             if (key <= tq) {
;                 const unsigned bin = (unsigned)(int)fminf(fmaxf(sa * 32.f + 128.f, 0.f), 255.f);
;                 if (PASS == 1) { if (bin >= b0) atomicAdd(&myhist[fq * 256 + bin], 1u); }
.LBB0_182:
	s_and_b32 s62, s4, 0x8000
	v_add_u32_e32 v64, s62, v134
	v_add_u32_e32 v122, v64, v135
	v_add_u32_e32 v123, v64, v136
	ds_read_b128 v[32:35], v122
	ds_read_b128 v[36:39], v123
	ds_read_b128 v[40:43], v122 offset:2048
	ds_read_b128 v[44:47], v123 offset:2048
	v_lshlrev_b32_e32 v121, 8, v121
	v_sub_u32_e32 v121, v115, v121
	v_sub_u32_e32 v78, v192, v121
	v_mov_b32_e32 v79, 0x437f0000
	v_mov_b32_e32 v88, 0x50005000
	s_mov_b32 s62, 0x100001
	s_mov_b32 s63, 0x10000100
	v_pk_mul_f16 v80, v193, v88
	v_pk_mul_f16 v81, v194, v88
	v_pk_mul_f16 v82, v195, v88
	v_pk_mul_f16 v83, v196, v88
	v_cndmask_b32_e64 v80, 0, v80, s[62:63]
	v_cndmask_b32_e64 v81, 0, v81, s[62:63]
	v_cndmask_b32_e64 v82, 0, v82, s[62:63]
	v_cndmask_b32_e64 v83, 0, v83, s[62:63]
	v_mov_b32_e32 v84, 0x43000000
	v_mov_b32_e32 v85, 0
	v_mov_b32_e32 v86, 0
	v_mov_b32_e32 v87, 0
	s_waitcnt lgkmcnt(2)
	v_mfma_f32_16x16x32_f16 v[48:51], v[0:3], v[32:35], 0
	v_mfma_f32_16x16x32_f16 v[52:55], v[8:11], v[32:35], 0
	v_mfma_f32_16x16x32_f16 v[48:51], v[4:7], v[36:39], v[48:51]
	v_mfma_f32_16x16x32_f16 v[52:55], v[12:15], v[36:39], v[52:55]
	s_nop 3
	ds_read_b128 v[32:35], v122 offset:4096
	ds_read_b128 v[36:39], v123 offset:4096
	s_waitcnt lgkmcnt(2)
	v_mfma_f32_16x16x32_f16 v[56:59], v[0:3], v[40:43], 0
	v_cvt_pkrtz_f16_f32 v67, v54, v55
	v_cvt_pkrtz_f16_f32 v66, v52, v53
	v_pk_max_f16 v67, v67, 0
	v_pk_max_f16 v66, v66, 0
	v_mfma_f32_16x16x32_f16 v[60:63], v[8:11], v[40:43], 0
	v_cvt_pkrtz_f16_f32 v65, v50, v51
	v_cvt_pkrtz_f16_f32 v64, v48, v49
	v_pk_max_f16 v65, v65, 0
	v_mfma_f32_16x16x32_f16 v[56:59], v[4:7], v[44:47], v[56:59]
	v_pk_max_f16 v64, v64, 0
	v_mfma_f32_16x16x32_f16 v[60:63], v[12:15], v[44:47], v[60:63]
	s_nop 3
	v_mfma_f32_16x16x32_f16 v[68:71], v[80:83], v[64:67], v[84:87]
	ds_read_b128 v[40:43], v122 offset:6144
	ds_read_b128 v[44:47], v123 offset:6144
	s_waitcnt lgkmcnt(2)
	v_mfma_f32_16x16x32_f16 v[48:51], v[0:3], v[32:35], 0
	v_cvt_pkrtz_f16_f32 v67, v62, v63
	v_cvt_pkrtz_f16_f32 v66, v60, v61
	v_pk_max_f16 v67, v67, 0
	v_pk_max_f16 v66, v66, 0
	v_mfma_f32_16x16x32_f16 v[52:55], v[8:11], v[32:35], 0
	v_cvt_pkrtz_f16_f32 v65, v58, v59
	v_cvt_pkrtz_f16_f32 v64, v56, v57
	v_med3_f32 v76, v68, 0, v79
	v_pk_max_f16 v65, v65, 0
	v_mfma_f32_16x16x32_f16 v[48:51], v[4:7], v[36:39], v[48:51]
	v_pk_max_f16 v64, v64, 0
	v_cvt_u32_f32_e32 v76, v76
	v_cmp_le_i32_e32 vcc, -240, v78
	v_mfma_f32_16x16x32_f16 v[52:55], v[12:15], v[36:39], v[52:55]
	v_lshl_add_u32 v77, v76, 2, v139
	s_and_b64 exec, exec, vcc
	ds_add_u32 v77, v212
	s_mov_b64 exec, -1
	v_mfma_f32_16x16x32_f16 v[72:75], v[80:83], v[64:67], v[84:87]
	ds_read_b128 v[32:35], v122 offset:8192
	ds_read_b128 v[36:39], v123 offset:8192
	s_waitcnt lgkmcnt(3)
	v_mfma_f32_16x16x32_f16 v[56:59], v[0:3], v[40:43], 0
	v_cvt_pkrtz_f16_f32 v67, v54, v55
	v_cvt_pkrtz_f16_f32 v66, v52, v53
	v_pk_max_f16 v67, v67, 0
	v_pk_max_f16 v66, v66, 0
	v_mfma_f32_16x16x32_f16 v[60:63], v[8:11], v[40:43], 0
	v_cvt_pkrtz_f16_f32 v65, v50, v51
	v_cvt_pkrtz_f16_f32 v64, v48, v49
	v_med3_f32 v76, v72, 0, v79
	v_pk_max_f16 v65, v65, 0
	v_mfma_f32_16x16x32_f16 v[56:59], v[4:7], v[44:47], v[56:59]
	v_pk_max_f16 v64, v64, 0
	v_cvt_u32_f32_e32 v76, v76
	v_cmp_le_i32_e32 vcc, -224, v78
	v_mfma_f32_16x16x32_f16 v[60:63], v[12:15], v[44:47], v[60:63]
	v_lshl_add_u32 v77, v76, 2, v139
	s_and_b64 exec, exec, vcc
	ds_add_u32 v77, v212
	s_mov_b64 exec, -1
	v_mfma_f32_16x16x32_f16 v[68:71], v[80:83], v[64:67], v[84:87]
	ds_read_b128 v[40:43], v122 offset:10240
	ds_read_b128 v[44:47], v123 offset:10240
	s_waitcnt lgkmcnt(3)
	v_mfma_f32_16x16x32_f16 v[48:51], v[0:3], v[32:35], 0
	v_cvt_pkrtz_f16_f32 v67, v62, v63
	v_cvt_pkrtz_f16_f32 v66, v60, v61
	v_pk_max_f16 v67, v67, 0
	v_pk_max_f16 v66, v66, 0
	v_mfma_f32_16x16x32_f16 v[52:55], v[8:11], v[32:35], 0
	v_cvt_pkrtz_f16_f32 v65, v58, v59
	v_cvt_pkrtz_f16_f32 v64, v56, v57
	v_med3_f32 v76, v68, 0, v79
	v_pk_max_f16 v65, v65, 0
	v_mfma_f32_16x16x32_f16 v[48:51], v[4:7], v[36:39], v[48:51]
	v_pk_max_f16 v64, v64, 0
	v_cvt_u32_f32_e32 v76, v76
	v_cmp_le_i32_e32 vcc, -208, v78
	v_mfma_f32_16x16x32_f16 v[52:55], v[12:15], v[36:39], v[52:55]
	v_lshl_add_u32 v77, v76, 2, v139
	s_and_b64 exec, exec, vcc
	ds_add_u32 v77, v212
	s_mov_b64 exec, -1
	v_mfma_f32_16x16x32_f16 v[72:75], v[80:83], v[64:67], v[84:87]
	ds_read_b128 v[32:35], v122 offset:12288
	ds_read_b128 v[36:39], v123 offset:12288
	s_waitcnt lgkmcnt(3)
	v_mfma_f32_16x16x32_f16 v[56:59], v[0:3], v[40:43], 0
	v_cvt_pkrtz_f16_f32 v67, v54, v55
	v_cvt_pkrtz_f16_f32 v66, v52, v53
	v_pk_max_f16 v67, v67, 0
	v_pk_max_f16 v66, v66, 0
	v_mfma_f32_16x16x32_f16 v[60:63], v[8:11], v[40:43], 0
	v_cvt_pkrtz_f16_f32 v65, v50, v51
	v_cvt_pkrtz_f16_f32 v64, v48, v49
	v_med3_f32 v76, v72, 0, v79
	v_pk_max_f16 v65, v65, 0
	v_mfma_f32_16x16x32_f16 v[56:59], v[4:7], v[44:47], v[56:59]
	v_pk_max_f16 v64, v64, 0
	v_cvt_u32_f32_e32 v76, v76
	v_cmp_le_i32_e32 vcc, -192, v78
	v_mfma_f32_16x16x32_f16 v[60:63], v[12:15], v[44:47], v[60:63]
	v_lshl_add_u32 v77, v76, 2, v139
	s_and_b64 exec, exec, vcc
	ds_add_u32 v77, v212
	s_mov_b64 exec, -1
	v_mfma_f32_16x16x32_f16 v[68:71], v[80:83], v[64:67], v[84:87]
	ds_read_b128 v[40:43], v122 offset:14336
	ds_read_b128 v[44:47], v123 offset:14336
	s_waitcnt lgkmcnt(3)
; template <int PASS> ...
;     ...
;         for (int e = 0; e < 8; ++e) { const int T = Tbase + hb * 8 + e;
;             f32x4 a0 = (f32x4){0.f, 0.f, 0.f, 0.f}, a1 = a0;
;             a0 = __builtin_amdgcn_mfma_f32_16x16x32_f16(aq[0][0], kf[e][0], a0, 0, 0, 0); a0 = __builtin_amdgcn_mfma_f32_16x16x32_f16(aq[0][1], kf[e][1], a0, 0, 0, 0);
;             a1 = __builtin_amdgcn_mfma_f32_16x16x32_f16(aq[1][0], kf[e][0], a1, 0, 0, 0); a1 = __builtin_amdgcn_mfma_f32_16x16x32_f16(aq[1][1], kf[e][1], a1, 0, 0, 0);
;             const h16x2 z2 = (h16x2){(h16)0.f, (h16)0.f};
;             const h16x2 r0 = __builtin_elementwise_max(__builtin_bit_cast(h16x2, __builtin_amdgcn_cvt_pkrtz(a0[0], a0[1])), z2), r1 = __builtin_elementwise_max(__builtin_bit_cast(h16x2, __builtin_amdgcn_cvt_pkrtz(a0[2], a0[3])), z2);
;             const h16x2 r2 = __builtin_elementwise_max(__builtin_bit_cast(h16x2, __builtin_amdgcn_cvt_pkrtz(a1[0], a1[1])), z2), r3 = __builtin_elementwise_max(__builtin_bit_cast(h16x2, __builtin_amdgcn_cvt_pkrtz(a1[2], a1[3])), z2);
;             const float sa = __builtin_amdgcn_fdot2(r0, wp[0], __builtin_amdgcn_fdot2(r1, wp[1], __builtin_amdgcn_fdot2(r2, wp[2], __builtin_amdgcn_fdot2(r3, wp[3], 0.f, false), false), false), false);
;             const int key = 16 * T + fr;
;             if (key <= tq) {
;                 const unsigned bin = (unsigned)(int)fminf(fmaxf(sa * 32.f + 128.f, 0.f), 255.f);
;                 if (PASS == 1) { if (bin >= b0) atomicAdd(&myhist[fq * 256 + bin], 1u); }
	v_mfma_f32_16x16x32_f16 v[48:51], v[0:3], v[32:35], 0
	v_cvt_pkrtz_f16_f32 v67, v62, v63
	v_cvt_pkrtz_f16_f32 v66, v60, v61
	v_pk_max_f16 v67, v67, 0
	v_pk_max_f16 v66, v66, 0
	v_mfma_f32_16x16x32_f16 v[52:55], v[8:11], v[32:35], 0
	v_cvt_pkrtz_f16_f32 v65, v58, v59
	v_cvt_pkrtz_f16_f32 v64, v56, v57
	v_med3_f32 v76, v68, 0, v79
	v_pk_max_f16 v65, v65, 0
	v_mfma_f32_16x16x32_f16 v[48:51], v[4:7], v[36:39], v[48:51]
	v_pk_max_f16 v64, v64, 0
	v_cvt_u32_f32_e32 v76, v76
	v_cmp_le_i32_e32 vcc, -176, v78
	v_mfma_f32_16x16x32_f16 v[52:55], v[12:15], v[36:39], v[52:55]
	v_lshl_add_u32 v77, v76, 2, v139
	s_and_b64 exec, exec, vcc
	ds_add_u32 v77, v212
	s_mov_b64 exec, -1
	v_mfma_f32_16x16x32_f16 v[72:75], v[80:83], v[64:67], v[84:87]
	ds_read_b128 v[32:35], v122 offset:16384
	ds_read_b128 v[36:39], v123 offset:16384
	s_waitcnt lgkmcnt(3)
	v_mfma_f32_16x16x32_f16 v[56:59], v[0:3], v[40:43], 0
	v_cvt_pkrtz_f16_f32 v67, v54, v55
	v_cvt_pkrtz_f16_f32 v66, v52, v53
	v_pk_max_f16 v67, v67, 0
	v_pk_max_f16 v66, v66, 0
	v_mfma_f32_16x16x32_f16 v[60:63], v[8:11], v[40:43], 0
	v_cvt_pkrtz_f16_f32 v65, v50, v51
	v_cvt_pkrtz_f16_f32 v64, v48, v49
	v_med3_f32 v76, v72, 0, v79
	v_pk_max_f16 v65, v65, 0
	v_mfma_f32_16x16x32_f16 v[56:59], v[4:7], v[44:47], v[56:59]
	v_pk_max_f16 v64, v64, 0
	v_cvt_u32_f32_e32 v76, v76
	v_cmp_le_i32_e32 vcc, -160, v78
	v_mfma_f32_16x16x32_f16 v[60:63], v[12:15], v[44:47], v[60:63]
	v_lshl_add_u32 v77, v76, 2, v139
	s_and_b64 exec, exec, vcc
	ds_add_u32 v77, v212
	s_mov_b64 exec, -1
	v_mfma_f32_16x16x32_f16 v[68:71], v[80:83], v[64:67], v[84:87]
	ds_read_b128 v[40:43], v122 offset:18432
	ds_read_b128 v[44:47], v123 offset:18432
	s_waitcnt lgkmcnt(3)
	v_mfma_f32_16x16x32_f16 v[48:51], v[0:3], v[32:35], 0
	v_cvt_pkrtz_f16_f32 v67, v62, v63
	v_cvt_pkrtz_f16_f32 v66, v60, v61
	v_pk_max_f16 v67, v67, 0
	v_pk_max_f16 v66, v66, 0
	v_mfma_f32_16x16x32_f16 v[52:55], v[8:11], v[32:35], 0
	v_cvt_pkrtz_f16_f32 v65, v58, v59
	v_cvt_pkrtz_f16_f32 v64, v56, v57
	v_med3_f32 v76, v68, 0, v79
	v_pk_max_f16 v65, v65, 0
	v_mfma_f32_16x16x32_f16 v[48:51], v[4:7], v[36:39], v[48:51]
	v_pk_max_f16 v64, v64, 0
	v_cvt_u32_f32_e32 v76, v76
	v_cmp_le_i32_e32 vcc, -144, v78
	v_mfma_f32_16x16x32_f16 v[52:55], v[12:15], v[36:39], v[52:55]
	v_lshl_add_u32 v77, v76, 2, v139
	s_and_b64 exec, exec, vcc
	ds_add_u32 v77, v212
	s_mov_b64 exec, -1
	v_mfma_f32_16x16x32_f16 v[72:75], v[80:83], v[64:67], v[84:87]
	ds_read_b128 v[32:35], v122 offset:20480
	ds_read_b128 v[36:39], v123 offset:20480
	s_waitcnt lgkmcnt(3)
	v_mfma_f32_16x16x32_f16 v[56:59], v[0:3], v[40:43], 0
	v_cvt_pkrtz_f16_f32 v67, v54, v55
	v_cvt_pkrtz_f16_f32 v66, v52, v53
	v_pk_max_f16 v67, v67, 0
	v_pk_max_f16 v66, v66, 0
	v_mfma_f32_16x16x32_f16 v[60:63], v[8:11], v[40:43], 0
	v_cvt_pkrtz_f16_f32 v65, v50, v51
	v_cvt_pkrtz_f16_f32 v64, v48, v49
	v_med3_f32 v76, v72, 0, v79
	v_pk_max_f16 v65, v65, 0
	v_mfma_f32_16x16x32_f16 v[56:59], v[4:7], v[44:47], v[56:59]
	v_pk_max_f16 v64, v64, 0
	v_cvt_u32_f32_e32 v76, v76
	v_cmp_le_i32_e32 vcc, -128, v78
	v_mfma_f32_16x16x32_f16 v[60:63], v[12:15], v[44:47], v[60:63]
	v_lshl_add_u32 v77, v76, 2, v139
	s_and_b64 exec, exec, vcc
	ds_add_u32 v77, v212
	s_mov_b64 exec, -1
	v_mfma_f32_16x16x32_f16 v[68:71], v[80:83], v[64:67], v[84:87]
	ds_read_b128 v[40:43], v122 offset:22528
	ds_read_b128 v[44:47], v123 offset:22528
	s_waitcnt lgkmcnt(3)
	v_mfma_f32_16x16x32_f16 v[48:51], v[0:3], v[32:35], 0
	v_cvt_pkrtz_f16_f32 v67, v62, v63
	v_cvt_pkrtz_f16_f32 v66, v60, v61
	v_pk_max_f16 v67, v67, 0
	v_pk_max_f16 v66, v66, 0
	v_mfma_f32_16x16x32_f16 v[52:55], v[8:11], v[32:35], 0
	v_cvt_pkrtz_f16_f32 v65, v58, v59
	v_cvt_pkrtz_f16_f32 v64, v56, v57
	v_med3_f32 v76, v68, 0, v79
	v_pk_max_f16 v65, v65, 0
	v_mfma_f32_16x16x32_f16 v[48:51], v[4:7], v[36:39], v[48:51]
	v_pk_max_f16 v64, v64, 0
	v_cvt_u32_f32_e32 v76, v76
	v_cmp_le_i32_e32 vcc, -112, v78
	v_mfma_f32_16x16x32_f16 v[52:55], v[12:15], v[36:39], v[52:55]
	v_lshl_add_u32 v77, v76, 2, v139
	s_and_b64 exec, exec, vcc
	ds_add_u32 v77, v212
	s_mov_b64 exec, -1
	v_mfma_f32_16x16x32_f16 v[72:75], v[80:83], v[64:67], v[84:87]
	ds_read_b128 v[32:35], v122 offset:24576
	ds_read_b128 v[36:39], v123 offset:24576
	s_waitcnt lgkmcnt(3)
; template <int PASS> ...
;     ...
;         for (int e = 0; e < 8; ++e) { const int T = Tbase + hb * 8 + e;
;             f32x4 a0 = (f32x4){0.f, 0.f, 0.f, 0.f}, a1 = a0;
;             a0 = __builtin_amdgcn_mfma_f32_16x16x32_f16(aq[0][0], kf[e][0], a0, 0, 0, 0); a0 = __builtin_amdgcn_mfma_f32_16x16x32_f16(aq[0][1], kf[e][1], a0, 0, 0, 0);
;             a1 = __builtin_amdgcn_mfma_f32_16x16x32_f16(aq[1][0], kf[e][0], a1, 0, 0, 0); a1 = __builtin_amdgcn_mfma_f32_16x16x32_f16(aq[1][1], kf[e][1], a1, 0, 0, 0);
;             const h16x2 z2 = (h16x2){(h16)0.f, (h16)0.f};
;             const h16x2 r0 = __builtin_elementwise_max(__builtin_bit_cast(h16x2, __builtin_amdgcn_cvt_pkrtz(a0[0], a0[1])), z2), r1 = __builtin_elementwise_max(__builtin_bit_cast(h16x2, __builtin_amdgcn_cvt_pkrtz(a0[2], a0[3])), z2);
;             const h16x2 r2 = __builtin_elementwise_max(__builtin_bit_cast(h16x2, __builtin_amdgcn_cvt_pkrtz(a1[0], a1[1])), z2), r3 = __builtin_elementwise_max(__builtin_bit_cast(h16x2, __builtin_amdgcn_cvt_pkrtz(a1[2], a1[3])), z2);
;             const float sa = __builtin_amdgcn_fdot2(r0, wp[0], __builtin_amdgcn_fdot2(r1, wp[1], __builtin_amdgcn_fdot2(r2, wp[2], __builtin_amdgcn_fdot2(r3, wp[3], 0.f, false), false), false), false);
;             const int key = 16 * T + fr;
;             if (key <= tq) {
;                 const unsigned bin = (unsigned)(int)fminf(fmaxf(sa * 32.f + 128.f, 0.f), 255.f);
;                 if (PASS == 1) { if (bin >= b0) atomicAdd(&myhist[fq * 256 + bin], 1u); }
	v_mfma_f32_16x16x32_f16 v[56:59], v[0:3], v[40:43], 0
	v_cvt_pkrtz_f16_f32 v67, v54, v55
	v_cvt_pkrtz_f16_f32 v66, v52, v53
	v_pk_max_f16 v67, v67, 0
	v_pk_max_f16 v66, v66, 0
	v_mfma_f32_16x16x32_f16 v[60:63], v[8:11], v[40:43], 0
	v_cvt_pkrtz_f16_f32 v65, v50, v51
	v_cvt_pkrtz_f16_f32 v64, v48, v49
	v_med3_f32 v76, v72, 0, v79
	v_pk_max_f16 v65, v65, 0
	v_mfma_f32_16x16x32_f16 v[56:59], v[4:7], v[44:47], v[56:59]
	v_pk_max_f16 v64, v64, 0
	v_cvt_u32_f32_e32 v76, v76
	v_cmp_le_i32_e32 vcc, -96, v78
	v_mfma_f32_16x16x32_f16 v[60:63], v[12:15], v[44:47], v[60:63]
	v_lshl_add_u32 v77, v76, 2, v139
	s_and_b64 exec, exec, vcc
	ds_add_u32 v77, v212
	s_mov_b64 exec, -1
	v_mfma_f32_16x16x32_f16 v[68:71], v[80:83], v[64:67], v[84:87]
	ds_read_b128 v[40:43], v122 offset:26624
	ds_read_b128 v[44:47], v123 offset:26624
	s_waitcnt lgkmcnt(3)
	v_mfma_f32_16x16x32_f16 v[48:51], v[0:3], v[32:35], 0
	v_cvt_pkrtz_f16_f32 v67, v62, v63
	v_cvt_pkrtz_f16_f32 v66, v60, v61
	v_pk_max_f16 v67, v67, 0
	v_pk_max_f16 v66, v66, 0
	v_mfma_f32_16x16x32_f16 v[52:55], v[8:11], v[32:35], 0
	v_cvt_pkrtz_f16_f32 v65, v58, v59
	v_cvt_pkrtz_f16_f32 v64, v56, v57
	v_med3_f32 v76, v68, 0, v79
	v_pk_max_f16 v65, v65, 0
	v_mfma_f32_16x16x32_f16 v[48:51], v[4:7], v[36:39], v[48:51]
	v_pk_max_f16 v64, v64, 0
	v_cvt_u32_f32_e32 v76, v76
	v_cmp_le_i32_e32 vcc, -80, v78
	v_mfma_f32_16x16x32_f16 v[52:55], v[12:15], v[36:39], v[52:55]
	v_lshl_add_u32 v77, v76, 2, v139
	s_and_b64 exec, exec, vcc
	ds_add_u32 v77, v212
	s_mov_b64 exec, -1
	v_mfma_f32_16x16x32_f16 v[72:75], v[80:83], v[64:67], v[84:87]
	ds_read_b128 v[32:35], v122 offset:28672
	ds_read_b128 v[36:39], v123 offset:28672
	s_waitcnt lgkmcnt(3)
	v_mfma_f32_16x16x32_f16 v[56:59], v[0:3], v[40:43], 0
	v_cvt_pkrtz_f16_f32 v67, v54, v55
	v_cvt_pkrtz_f16_f32 v66, v52, v53
	v_pk_max_f16 v67, v67, 0
	v_pk_max_f16 v66, v66, 0
	v_mfma_f32_16x16x32_f16 v[60:63], v[8:11], v[40:43], 0
	v_cvt_pkrtz_f16_f32 v65, v50, v51
	v_cvt_pkrtz_f16_f32 v64, v48, v49
	v_med3_f32 v76, v72, 0, v79
	v_pk_max_f16 v65, v65, 0
	v_mfma_f32_16x16x32_f16 v[56:59], v[4:7], v[44:47], v[56:59]
	v_pk_max_f16 v64, v64, 0
	v_cvt_u32_f32_e32 v76, v76
	v_cmp_le_i32_e32 vcc, -64, v78
	v_mfma_f32_16x16x32_f16 v[60:63], v[12:15], v[44:47], v[60:63]
	v_lshl_add_u32 v77, v76, 2, v139
	s_and_b64 exec, exec, vcc
	ds_add_u32 v77, v212
	s_mov_b64 exec, -1
	v_mfma_f32_16x16x32_f16 v[68:71], v[80:83], v[64:67], v[84:87]
	ds_read_b128 v[40:43], v122 offset:30720
	ds_read_b128 v[44:47], v123 offset:30720
	s_waitcnt lgkmcnt(3)
	v_mfma_f32_16x16x32_f16 v[48:51], v[0:3], v[32:35], 0
	v_cvt_pkrtz_f16_f32 v67, v62, v63
	v_cvt_pkrtz_f16_f32 v66, v60, v61
	v_pk_max_f16 v67, v67, 0
	v_pk_max_f16 v66, v66, 0
	v_mfma_f32_16x16x32_f16 v[52:55], v[8:11], v[32:35], 0
	v_cvt_pkrtz_f16_f32 v65, v58, v59
	v_cvt_pkrtz_f16_f32 v64, v56, v57
	v_med3_f32 v76, v68, 0, v79
	v_pk_max_f16 v65, v65, 0
	v_mfma_f32_16x16x32_f16 v[48:51], v[4:7], v[36:39], v[48:51]
	v_pk_max_f16 v64, v64, 0
	v_cvt_u32_f32_e32 v76, v76
	v_cmp_le_i32_e32 vcc, -48, v78
	v_mfma_f32_16x16x32_f16 v[52:55], v[12:15], v[36:39], v[52:55]
	v_lshl_add_u32 v77, v76, 2, v139
	s_and_b64 exec, exec, vcc
	ds_add_u32 v77, v212
	s_mov_b64 exec, -1
	v_mfma_f32_16x16x32_f16 v[72:75], v[80:83], v[64:67], v[84:87]
	s_nop 3
	s_waitcnt lgkmcnt(1)
	v_mfma_f32_16x16x32_f16 v[56:59], v[0:3], v[40:43], 0
	v_cvt_pkrtz_f16_f32 v67, v54, v55
	v_cvt_pkrtz_f16_f32 v66, v52, v53
	v_pk_max_f16 v67, v67, 0
	v_pk_max_f16 v66, v66, 0
	v_mfma_f32_16x16x32_f16 v[60:63], v[8:11], v[40:43], 0
	v_cvt_pkrtz_f16_f32 v65, v50, v51
	v_cvt_pkrtz_f16_f32 v64, v48, v49
	v_med3_f32 v76, v72, 0, v79
	v_pk_max_f16 v65, v65, 0
	v_mfma_f32_16x16x32_f16 v[56:59], v[4:7], v[44:47], v[56:59]
	v_pk_max_f16 v64, v64, 0
	v_cvt_u32_f32_e32 v76, v76
	v_cmp_le_i32_e32 vcc, -32, v78
	v_mfma_f32_16x16x32_f16 v[60:63], v[12:15], v[44:47], v[60:63]
	v_lshl_add_u32 v77, v76, 2, v139
	s_and_b64 exec, exec, vcc
	ds_add_u32 v77, v212
	s_mov_b64 exec, -1
	v_mfma_f32_16x16x32_f16 v[68:71], v[80:83], v[64:67], v[84:87]
	s_nop 3
	v_cvt_pkrtz_f16_f32 v67, v62, v63
	v_cvt_pkrtz_f16_f32 v66, v60, v61
	v_pk_max_f16 v67, v67, 0
	v_pk_max_f16 v66, v66, 0
	v_cvt_pkrtz_f16_f32 v65, v58, v59
	v_cvt_pkrtz_f16_f32 v64, v56, v57
	v_med3_f32 v76, v68, 0, v79
	v_pk_max_f16 v65, v65, 0
	v_pk_max_f16 v64, v64, 0
	v_cvt_u32_f32_e32 v76, v76
	v_cmp_le_i32_e32 vcc, -16, v78
	v_lshl_add_u32 v77, v76, 2, v139
	s_and_b64 exec, exec, vcc
	ds_add_u32 v77, v212
	s_mov_b64 exec, -1
	v_mfma_f32_16x16x32_f16 v[72:75], v[80:83], v[64:67], v[84:87]
	s_nop 7
	s_nop 3
	v_med3_f32 v76, v72, 0, v79
	v_cvt_u32_f32_e32 v76, v76
	v_cmp_le_i32_e32 vcc, 0, v78
	v_lshl_add_u32 v77, v76, 2, v139
	s_and_b64 exec, exec, vcc
	ds_add_u32 v77, v212
	s_mov_b64 exec, -1
	s_branch .LBB0_239

; template <int PASS> ...
;     ...
;         for (int e = 0; e < 8; ++e) { const int T = Tbase + hb * 8 + e;
;             f32x4 a0 = (f32x4){0.f, 0.f, 0.f, 0.f}, a1 = a0;
;             a0 = __builtin_amdgcn_mfma_f32_16x16x32_f16(aq[0][0], kf[e][0], a0, 0, 0, 0); a0 = __builtin_amdgcn_mfma_f32_16x16x32_f16(aq[0][1], kf[e][1], a0, 0, 0, 0);
;             a1 = __builtin_amdgcn_mfma_f32_16x16x32_f16(aq[1][0], kf[e][0], a1, 0, 0, 0); a1 = __builtin_amdgcn_mfma_f32_16x16x32_f16(aq[1][1], kf[e][1], a1, 0, 0, 0);
;             const h16x2 z2 = (h16x2){(h16)0.f, (h16)0.f};
;             const h16x2 r0 = __builtin_elementwise_max(__builtin_bit_cast(h16x2, __builtin_amdgcn_cvt_pkrtz(a0[0], a0[1])), z2), r1 = __builtin_elementwise_max(__builtin_bit_cast(h16x2, __builtin_amdgcn_cvt_pkrtz(a0[2], a0[3])), z2);
;             const h16x2 r2 = __builtin_elementwise_max(__builtin_bit_cast(h16x2, __builtin_amdgcn_cvt_pkrtz(a1[0], a1[1])), z2), r3 = __builtin_elementwise_max(__builtin_bit_cast(h16x2, __builtin_amdgcn_cvt_pkrtz(a1[2], a1[3])), z2);
;             const float sa = __builtin_amdgcn_fdot2(r0, wp[0], __builtin_amdgcn_fdot2(r1, wp[1], __builtin_amdgcn_fdot2(r2, wp[2], __builtin_amdgcn_fdot2(r3, wp[3], 0.f, false), false), false), false);
;             const int key = 16 * T + fr;
;             if (key <= tq) {
;                 const unsigned bin = (unsigned)(int)fminf(fmaxf(sa * 32.f + 128.f, 0.f), 255.f);
;                 if (PASS == 1) { if (bin >= b0) atomicAdd(&myhist[fq * 256 + bin], 1u); }
;                 else {
;                     if (bin > b0) { const unsigned pos = atomicAdd(&myctl[fq * 4 + 2], 1u); ((unsigned short*)myhist)[fq * 256 + (pos & 255u)] = (unsigned short)key; }
;                     else if (bin == b0) { const unsigned c = atomicAdd(&myctl[fq * 4 + 3], 1u);
;                         if (c < 128u) { float s = 0.f;
; #pragma unroll
;                             for (int r = 0; r < 4; ++r) s += wv[r] * fmaxf(a0[r], 0.f) + wv[4 + r] * fmaxf(a1[r], 0.f);
;                             s = fminf(fmaxf(s, -3.99f), 3.99f);
;                             mycand[(fq * 128 + c) * 2] = (unsigned)((s + 4.f) * 536870912.f); mycand[(fq * 128 + c) * 2 + 1] = (unsigned)key; } }
.LBB0_293:
	s_and_b32 s4, s85, 0x8000
	v_add_u32_e32 v72, s4, v134
	v_add_u32_e32 v118, v72, v135
	v_add_u32_e32 v119, v72, v136
	ds_read_b128 v[32:35], v118
	ds_read_b128 v[36:39], v119
	ds_read_b128 v[40:43], v118 offset:2048
	ds_read_b128 v[44:47], v119 offset:2048
	v_lshlrev_b32_e32 v116, 8, v116
	v_sub_u32_e32 v117, v121, v116
	v_sub_u32_e32 v93, v192, v117
	v_cvt_f32_u32_e32 v94, v120
	v_cmp_eq_u32_e32 vcc, 0, v120
	v_add_f32_e32 v95, 1.0, v94
	v_mov_b32_e32 v92, 0
	v_mov_b32_e32 v123, 0xff800000
	v_cndmask_b32_e32 v94, v94, v123, vcc
	v_cmp_lt_u32_e32 vcc, 0xfe, v120
	v_mov_b32_e32 v123, 0x7f800000
	v_subrev_u32_e32 v122, 0x100, v117
	v_cndmask_b32_e32 v95, v95, v123, vcc
	v_bfrev_b32_e32 v123, 1
	v_mov_b32_e32 v202, 0x50005000
	s_mov_b32 s60, 0x100001
	s_mov_b32 s61, 0x10000100
	v_pk_mul_f16 v84, v193, v202
	v_pk_mul_f16 v85, v194, v202
	v_pk_mul_f16 v86, v195, v202
	v_pk_mul_f16 v87, v196, v202
	v_cndmask_b32_e64 v84, 0, v84, s[60:61]
	v_cndmask_b32_e64 v85, 0, v85, s[60:61]
	v_cndmask_b32_e64 v86, 0, v86, s[60:61]
	v_cndmask_b32_e64 v87, 0, v87, s[60:61]
	v_mov_b32_e32 v88, 0x43000000
	v_mov_b32_e32 v89, 0
	v_mov_b32_e32 v90, 0
	v_mov_b32_e32 v91, 0
	s_waitcnt lgkmcnt(2)
	v_mfma_f32_16x16x32_f16 v[48:51], v[0:3], v[32:35], 0
	v_mfma_f32_16x16x32_f16 v[52:55], v[8:11], v[32:35], 0
	v_mfma_f32_16x16x32_f16 v[48:51], v[4:7], v[36:39], v[48:51]
	v_mfma_f32_16x16x32_f16 v[52:55], v[12:15], v[36:39], v[52:55]
	s_nop 3
	ds_read_b128 v[32:35], v118 offset:4096
	ds_read_b128 v[36:39], v119 offset:4096
	s_waitcnt lgkmcnt(2)
	v_mfma_f32_16x16x32_f16 v[56:59], v[0:3], v[40:43], 0
	v_cvt_pkrtz_f16_f32 v75, v54, v55
	v_cvt_pkrtz_f16_f32 v74, v52, v53
	v_pk_max_f16 v75, v75, 0
	v_pk_max_f16 v74, v74, 0
	v_mfma_f32_16x16x32_f16 v[60:63], v[8:11], v[40:43], 0
	v_cvt_pkrtz_f16_f32 v73, v50, v51
	v_cvt_pkrtz_f16_f32 v72, v48, v49
	v_pk_max_f16 v73, v73, 0
	v_mfma_f32_16x16x32_f16 v[56:59], v[4:7], v[44:47], v[56:59]
	v_pk_max_f16 v72, v72, 0
	v_mfma_f32_16x16x32_f16 v[60:63], v[12:15], v[44:47], v[60:63]
	s_nop 3
	v_mfma_f32_16x16x32_f16 v[76:79], v[84:87], v[72:75], v[88:91]
	ds_read_b128 v[40:43], v118 offset:6144
	ds_read_b128 v[44:47], v119 offset:6144
	s_waitcnt lgkmcnt(2)
	v_mfma_f32_16x16x32_f16 v[64:67], v[0:3], v[32:35], 0
	v_cvt_pkrtz_f16_f32 v75, v62, v63
	v_cvt_pkrtz_f16_f32 v74, v60, v61
	v_pk_max_f16 v75, v75, 0
	v_pk_max_f16 v74, v74, 0
	v_mfma_f32_16x16x32_f16 v[68:71], v[8:11], v[32:35], 0
	v_cvt_pkrtz_f16_f32 v73, v58, v59
	v_cvt_pkrtz_f16_f32 v72, v56, v57
	v_cmp_le_i32_e32 vcc, 0, v93
	v_pk_max_f16 v73, v73, 0
	v_mfma_f32_16x16x32_f16 v[64:67], v[4:7], v[36:39], v[64:67]
	v_pk_max_f16 v72, v72, 0
	v_cmp_le_f32_e64 s[60:61], v95, v76
	v_cmp_le_f32_e64 s[62:63], v94, v76
	v_mfma_f32_16x16x32_f16 v[68:71], v[12:15], v[36:39], v[68:71]
	v_mfma_f32_16x16x32_f16 v[80:83], v[84:87], v[72:75], v[88:91]
	s_and_b64 s[62:63], s[62:63], vcc
	s_and_b64 vcc, vcc, s[60:61]
	v_addc_co_u32_e32 v92, vcc, v92, v92, vcc
	s_andn2_b64 s[62:63], s[62:63], s[60:61]
	s_cbranch_scc1 .Lp2_slow0
.Lp2_back0:
	ds_read_b128 v[32:35], v118 offset:8192
	ds_read_b128 v[36:39], v119 offset:8192
	s_waitcnt lgkmcnt(2)
	v_mfma_f32_16x16x32_f16 v[48:51], v[0:3], v[40:43], 0
	v_cvt_pkrtz_f16_f32 v75, v70, v71
	v_cvt_pkrtz_f16_f32 v74, v68, v69
	v_pk_max_f16 v75, v75, 0
	v_pk_max_f16 v74, v74, 0
	v_mfma_f32_16x16x32_f16 v[52:55], v[8:11], v[40:43], 0
	v_cvt_pkrtz_f16_f32 v73, v66, v67
	v_cvt_pkrtz_f16_f32 v72, v64, v65
	v_cmp_le_i32_e32 vcc, 16, v93
	v_pk_max_f16 v73, v73, 0
	v_mfma_f32_16x16x32_f16 v[48:51], v[4:7], v[44:47], v[48:51]
	v_pk_max_f16 v72, v72, 0
	v_cmp_le_f32_e64 s[60:61], v95, v80
	v_cmp_le_f32_e64 s[62:63], v94, v80
	v_mfma_f32_16x16x32_f16 v[52:55], v[12:15], v[44:47], v[52:55]
	v_mfma_f32_16x16x32_f16 v[76:79], v[84:87], v[72:75], v[88:91]
	s_and_b64 s[62:63], s[62:63], vcc
	s_and_b64 vcc, vcc, s[60:61]
	v_addc_co_u32_e32 v92, vcc, v92, v92, vcc
	s_andn2_b64 s[62:63], s[62:63], s[60:61]
	s_cbranch_scc1 .Lp2_slow1
.Lp2_back1:
	ds_read_b128 v[40:43], v118 offset:10240
	ds_read_b128 v[44:47], v119 offset:10240
	s_waitcnt lgkmcnt(2)
	v_mfma_f32_16x16x32_f16 v[56:59], v[0:3], v[32:35], 0
	v_cvt_pkrtz_f16_f32 v75, v54, v55
	v_cvt_pkrtz_f16_f32 v74, v52, v53
	v_pk_max_f16 v75, v75, 0
	v_pk_max_f16 v74, v74, 0
	v_mfma_f32_16x16x32_f16 v[60:63], v[8:11], v[32:35], 0
	v_cvt_pkrtz_f16_f32 v73, v50, v51
	v_cvt_pkrtz_f16_f32 v72, v48, v49
	v_cmp_le_i32_e32 vcc, 32, v93
	v_pk_max_f16 v73, v73, 0
	v_mfma_f32_16x16x32_f16 v[56:59], v[4:7], v[36:39], v[56:59]
	v_pk_max_f16 v72, v72, 0
	v_cmp_le_f32_e64 s[60:61], v95, v76
	v_cmp_le_f32_e64 s[62:63], v94, v76
	v_mfma_f32_16x16x32_f16 v[60:63], v[12:15], v[36:39], v[60:63]
	v_mfma_f32_16x16x32_f16 v[80:83], v[84:87], v[72:75], v[88:91]
	s_and_b64 s[62:63], s[62:63], vcc
	s_and_b64 vcc, vcc, s[60:61]
	v_addc_co_u32_e32 v92, vcc, v92, v92, vcc
	s_andn2_b64 s[62:63], s[62:63], s[60:61]
	s_cbranch_scc1 .Lp2_slow2
.Lp2_back2:
	ds_read_b128 v[32:35], v118 offset:12288
	ds_read_b128 v[36:39], v119 offset:12288
	s_waitcnt lgkmcnt(2)
	v_mfma_f32_16x16x32_f16 v[64:67], v[0:3], v[40:43], 0
	v_cvt_pkrtz_f16_f32 v75, v62, v63
	v_cvt_pkrtz_f16_f32 v74, v60, v61
	v_pk_max_f16 v75, v75, 0
	v_pk_max_f16 v74, v74, 0
	v_mfma_f32_16x16x32_f16 v[68:71], v[8:11], v[40:43], 0
	v_cvt_pkrtz_f16_f32 v73, v58, v59
	v_cvt_pkrtz_f16_f32 v72, v56, v57
	v_cmp_le_i32_e32 vcc, 48, v93
	v_pk_max_f16 v73, v73, 0
	v_mfma_f32_16x16x32_f16 v[64:67], v[4:7], v[44:47], v[64:67]
	v_pk_max_f16 v72, v72, 0
	v_cmp_le_f32_e64 s[60:61], v95, v80
	v_cmp_le_f32_e64 s[62:63], v94, v80
	v_mfma_f32_16x16x32_f16 v[68:71], v[12:15], v[44:47], v[68:71]
	v_mfma_f32_16x16x32_f16 v[76:79], v[84:87], v[72:75], v[88:91]
	s_and_b64 s[62:63], s[62:63], vcc
	s_and_b64 vcc, vcc, s[60:61]
	v_addc_co_u32_e32 v92, vcc, v92, v92, vcc
	s_andn2_b64 s[62:63], s[62:63], s[60:61]
	s_cbranch_scc1 .Lp2_slow3
; template <int PASS> ...
;     ...
;         for (int e = 0; e < 8; ++e) { const int T = Tbase + hb * 8 + e;
;             f32x4 a0 = (f32x4){0.f, 0.f, 0.f, 0.f}, a1 = a0;
;             a0 = __builtin_amdgcn_mfma_f32_16x16x32_f16(aq[0][0], kf[e][0], a0, 0, 0, 0); a0 = __builtin_amdgcn_mfma_f32_16x16x32_f16(aq[0][1], kf[e][1], a0, 0, 0, 0);
;             a1 = __builtin_amdgcn_mfma_f32_16x16x32_f16(aq[1][0], kf[e][0], a1, 0, 0, 0); a1 = __builtin_amdgcn_mfma_f32_16x16x32_f16(aq[1][1], kf[e][1], a1, 0, 0, 0);
;             const h16x2 z2 = (h16x2){(h16)0.f, (h16)0.f};
;             const h16x2 r0 = __builtin_elementwise_max(__builtin_bit_cast(h16x2, __builtin_amdgcn_cvt_pkrtz(a0[0], a0[1])), z2), r1 = __builtin_elementwise_max(__builtin_bit_cast(h16x2, __builtin_amdgcn_cvt_pkrtz(a0[2], a0[3])), z2);
;             const h16x2 r2 = __builtin_elementwise_max(__builtin_bit_cast(h16x2, __builtin_amdgcn_cvt_pkrtz(a1[0], a1[1])), z2), r3 = __builtin_elementwise_max(__builtin_bit_cast(h16x2, __builtin_amdgcn_cvt_pkrtz(a1[2], a1[3])), z2);
;             const float sa = __builtin_amdgcn_fdot2(r0, wp[0], __builtin_amdgcn_fdot2(r1, wp[1], __builtin_amdgcn_fdot2(r2, wp[2], __builtin_amdgcn_fdot2(r3, wp[3], 0.f, false), false), false), false);
;             const int key = 16 * T + fr;
;             if (key <= tq) {
;                 const unsigned bin = (unsigned)(int)fminf(fmaxf(sa * 32.f + 128.f, 0.f), 255.f);
;                 if (PASS == 1) { if (bin >= b0) atomicAdd(&myhist[fq * 256 + bin], 1u); }
;                 else {
;                     if (bin > b0) { const unsigned pos = atomicAdd(&myctl[fq * 4 + 2], 1u); ((unsigned short*)myhist)[fq * 256 + (pos & 255u)] = (unsigned short)key; }
;                     else if (bin == b0) { const unsigned c = atomicAdd(&myctl[fq * 4 + 3], 1u);
.Lp2_back3:
	ds_read_b128 v[40:43], v118 offset:14336
	ds_read_b128 v[44:47], v119 offset:14336
	s_waitcnt lgkmcnt(2)
	v_mfma_f32_16x16x32_f16 v[48:51], v[0:3], v[32:35], 0
	v_cvt_pkrtz_f16_f32 v75, v70, v71
	v_cvt_pkrtz_f16_f32 v74, v68, v69
	v_pk_max_f16 v75, v75, 0
	v_pk_max_f16 v74, v74, 0
	v_mfma_f32_16x16x32_f16 v[52:55], v[8:11], v[32:35], 0
	v_cvt_pkrtz_f16_f32 v73, v66, v67
	v_cvt_pkrtz_f16_f32 v72, v64, v65
	v_cmp_le_i32_e32 vcc, 64, v93
	v_pk_max_f16 v73, v73, 0
	v_mfma_f32_16x16x32_f16 v[48:51], v[4:7], v[36:39], v[48:51]
	v_pk_max_f16 v72, v72, 0
	v_cmp_le_f32_e64 s[60:61], v95, v76
	v_cmp_le_f32_e64 s[62:63], v94, v76
	v_mfma_f32_16x16x32_f16 v[52:55], v[12:15], v[36:39], v[52:55]
	v_mfma_f32_16x16x32_f16 v[80:83], v[84:87], v[72:75], v[88:91]
	s_and_b64 s[62:63], s[62:63], vcc
	s_and_b64 vcc, vcc, s[60:61]
	v_addc_co_u32_e32 v92, vcc, v92, v92, vcc
	s_andn2_b64 s[62:63], s[62:63], s[60:61]
	s_cbranch_scc1 .Lp2_slow4
.Lp2_back4:
	ds_read_b128 v[32:35], v118 offset:16384
	ds_read_b128 v[36:39], v119 offset:16384
	s_waitcnt lgkmcnt(2)
	v_mfma_f32_16x16x32_f16 v[56:59], v[0:3], v[40:43], 0
	v_cvt_pkrtz_f16_f32 v75, v54, v55
	v_cvt_pkrtz_f16_f32 v74, v52, v53
	v_pk_max_f16 v75, v75, 0
	v_pk_max_f16 v74, v74, 0
	v_mfma_f32_16x16x32_f16 v[60:63], v[8:11], v[40:43], 0
	v_cvt_pkrtz_f16_f32 v73, v50, v51
	v_cvt_pkrtz_f16_f32 v72, v48, v49
	v_cmp_le_i32_e32 vcc, 80, v93
	v_pk_max_f16 v73, v73, 0
	v_mfma_f32_16x16x32_f16 v[56:59], v[4:7], v[44:47], v[56:59]
	v_pk_max_f16 v72, v72, 0
	v_cmp_le_f32_e64 s[60:61], v95, v80
	v_cmp_le_f32_e64 s[62:63], v94, v80
	v_mfma_f32_16x16x32_f16 v[60:63], v[12:15], v[44:47], v[60:63]
	v_mfma_f32_16x16x32_f16 v[76:79], v[84:87], v[72:75], v[88:91]
	s_and_b64 s[62:63], s[62:63], vcc
	s_and_b64 vcc, vcc, s[60:61]
	v_addc_co_u32_e32 v92, vcc, v92, v92, vcc
	s_andn2_b64 s[62:63], s[62:63], s[60:61]
	s_cbranch_scc1 .Lp2_slow5
.Lp2_back5:
	ds_read_b128 v[40:43], v118 offset:18432
	ds_read_b128 v[44:47], v119 offset:18432
	s_waitcnt lgkmcnt(2)
	v_mfma_f32_16x16x32_f16 v[64:67], v[0:3], v[32:35], 0
	v_cvt_pkrtz_f16_f32 v75, v62, v63
	v_cvt_pkrtz_f16_f32 v74, v60, v61
	v_pk_max_f16 v75, v75, 0
	v_pk_max_f16 v74, v74, 0
	v_mfma_f32_16x16x32_f16 v[68:71], v[8:11], v[32:35], 0
	v_cvt_pkrtz_f16_f32 v73, v58, v59
	v_cvt_pkrtz_f16_f32 v72, v56, v57
	v_cmp_le_i32_e32 vcc, 96, v93
	v_pk_max_f16 v73, v73, 0
	v_mfma_f32_16x16x32_f16 v[64:67], v[4:7], v[36:39], v[64:67]
	v_pk_max_f16 v72, v72, 0
	v_cmp_le_f32_e64 s[60:61], v95, v76
	v_cmp_le_f32_e64 s[62:63], v94, v76
	v_mfma_f32_16x16x32_f16 v[68:71], v[12:15], v[36:39], v[68:71]
	v_mfma_f32_16x16x32_f16 v[80:83], v[84:87], v[72:75], v[88:91]
	s_and_b64 s[62:63], s[62:63], vcc
	s_and_b64 vcc, vcc, s[60:61]
	v_addc_co_u32_e32 v92, vcc, v92, v92, vcc
	s_andn2_b64 s[62:63], s[62:63], s[60:61]
	s_cbranch_scc1 .Lp2_slow6
.Lp2_back6:
	ds_read_b128 v[32:35], v118 offset:20480
	ds_read_b128 v[36:39], v119 offset:20480
	s_waitcnt lgkmcnt(2)
	v_mfma_f32_16x16x32_f16 v[48:51], v[0:3], v[40:43], 0
	v_cvt_pkrtz_f16_f32 v75, v70, v71
	v_cvt_pkrtz_f16_f32 v74, v68, v69
	v_pk_max_f16 v75, v75, 0
	v_pk_max_f16 v74, v74, 0
	v_mfma_f32_16x16x32_f16 v[52:55], v[8:11], v[40:43], 0
	v_cvt_pkrtz_f16_f32 v73, v66, v67
	v_cvt_pkrtz_f16_f32 v72, v64, v65
	v_cmp_le_i32_e32 vcc, 112, v93
	v_pk_max_f16 v73, v73, 0
	v_mfma_f32_16x16x32_f16 v[48:51], v[4:7], v[44:47], v[48:51]
	v_pk_max_f16 v72, v72, 0
	v_cmp_le_f32_e64 s[60:61], v95, v80
	v_cmp_le_f32_e64 s[62:63], v94, v80
	v_mfma_f32_16x16x32_f16 v[52:55], v[12:15], v[44:47], v[52:55]
	v_mfma_f32_16x16x32_f16 v[76:79], v[84:87], v[72:75], v[88:91]
	s_and_b64 s[62:63], s[62:63], vcc
	s_and_b64 vcc, vcc, s[60:61]
	v_addc_co_u32_e32 v92, vcc, v92, v92, vcc
	s_andn2_b64 s[62:63], s[62:63], s[60:61]
	s_cbranch_scc1 .Lp2_slow7
.Lp2_back7:
	ds_read_b128 v[40:43], v118 offset:22528
	ds_read_b128 v[44:47], v119 offset:22528
	s_waitcnt lgkmcnt(2)
	v_mfma_f32_16x16x32_f16 v[56:59], v[0:3], v[32:35], 0
	v_cvt_pkrtz_f16_f32 v75, v54, v55
	v_cvt_pkrtz_f16_f32 v74, v52, v53
	v_pk_max_f16 v75, v75, 0
	v_pk_max_f16 v74, v74, 0
	v_mfma_f32_16x16x32_f16 v[60:63], v[8:11], v[32:35], 0
	v_cvt_pkrtz_f16_f32 v73, v50, v51
	v_cvt_pkrtz_f16_f32 v72, v48, v49
	v_cmp_le_i32_e32 vcc, 128, v93
	v_pk_max_f16 v73, v73, 0
	v_mfma_f32_16x16x32_f16 v[56:59], v[4:7], v[36:39], v[56:59]
	v_pk_max_f16 v72, v72, 0
	v_cmp_le_f32_e64 s[60:61], v95, v76
	v_cmp_le_f32_e64 s[62:63], v94, v76
	v_mfma_f32_16x16x32_f16 v[60:63], v[12:15], v[36:39], v[60:63]
	v_mfma_f32_16x16x32_f16 v[80:83], v[84:87], v[72:75], v[88:91]
	s_and_b64 s[62:63], s[62:63], vcc
	s_and_b64 vcc, vcc, s[60:61]
	v_addc_co_u32_e32 v92, vcc, v92, v92, vcc
	s_andn2_b64 s[62:63], s[62:63], s[60:61]
	s_cbranch_scc1 .Lp2_slow8
.Lp2_back8:
	ds_read_b128 v[32:35], v118 offset:24576
	ds_read_b128 v[36:39], v119 offset:24576
	s_waitcnt lgkmcnt(2)
	v_mfma_f32_16x16x32_f16 v[64:67], v[0:3], v[40:43], 0
	v_cvt_pkrtz_f16_f32 v75, v62, v63
	v_cvt_pkrtz_f16_f32 v74, v60, v61
	v_pk_max_f16 v75, v75, 0
	v_pk_max_f16 v74, v74, 0
	v_mfma_f32_16x16x32_f16 v[68:71], v[8:11], v[40:43], 0
	v_cvt_pkrtz_f16_f32 v73, v58, v59
	v_cvt_pkrtz_f16_f32 v72, v56, v57
	v_cmp_le_i32_e32 vcc, 144, v93
	v_pk_max_f16 v73, v73, 0
	v_mfma_f32_16x16x32_f16 v[64:67], v[4:7], v[44:47], v[64:67]
	v_pk_max_f16 v72, v72, 0
	v_cmp_le_f32_e64 s[60:61], v95, v80
	v_cmp_le_f32_e64 s[62:63], v94, v80
	v_mfma_f32_16x16x32_f16 v[68:71], v[12:15], v[44:47], v[68:71]
	v_mfma_f32_16x16x32_f16 v[76:79], v[84:87], v[72:75], v[88:91]
	s_and_b64 s[62:63], s[62:63], vcc
	s_and_b64 vcc, vcc, s[60:61]
	v_addc_co_u32_e32 v92, vcc, v92, v92, vcc
	s_andn2_b64 s[62:63], s[62:63], s[60:61]
	s_cbranch_scc1 .Lp2_slow9
; template <int PASS> ...
;     ...
;         for (int e = 0; e < 8; ++e) { const int T = Tbase + hb * 8 + e;
;             f32x4 a0 = (f32x4){0.f, 0.f, 0.f, 0.f}, a1 = a0;
;             a0 = __builtin_amdgcn_mfma_f32_16x16x32_f16(aq[0][0], kf[e][0], a0, 0, 0, 0); a0 = __builtin_amdgcn_mfma_f32_16x16x32_f16(aq[0][1], kf[e][1], a0, 0, 0, 0);
;             a1 = __builtin_amdgcn_mfma_f32_16x16x32_f16(aq[1][0], kf[e][0], a1, 0, 0, 0); a1 = __builtin_amdgcn_mfma_f32_16x16x32_f16(aq[1][1], kf[e][1], a1, 0, 0, 0);
;             const h16x2 z2 = (h16x2){(h16)0.f, (h16)0.f};
;             const h16x2 r0 = __builtin_elementwise_max(__builtin_bit_cast(h16x2, __builtin_amdgcn_cvt_pkrtz(a0[0], a0[1])), z2), r1 = __builtin_elementwise_max(__builtin_bit_cast(h16x2, __builtin_amdgcn_cvt_pkrtz(a0[2], a0[3])), z2);
;             const h16x2 r2 = __builtin_elementwise_max(__builtin_bit_cast(h16x2, __builtin_amdgcn_cvt_pkrtz(a1[0], a1[1])), z2), r3 = __builtin_elementwise_max(__builtin_bit_cast(h16x2, __builtin_amdgcn_cvt_pkrtz(a1[2], a1[3])), z2);
;             const float sa = __builtin_amdgcn_fdot2(r0, wp[0], __builtin_amdgcn_fdot2(r1, wp[1], __builtin_amdgcn_fdot2(r2, wp[2], __builtin_amdgcn_fdot2(r3, wp[3], 0.f, false), false), false), false);
;             const int key = 16 * T + fr;
;             if (key <= tq) {
;                 const unsigned bin = (unsigned)(int)fminf(fmaxf(sa * 32.f + 128.f, 0.f), 255.f);
;                 if (PASS == 1) { if (bin >= b0) atomicAdd(&myhist[fq * 256 + bin], 1u); }
;                 else {
;                     if (bin > b0) { const unsigned pos = atomicAdd(&myctl[fq * 4 + 2], 1u); ((unsigned short*)myhist)[fq * 256 + (pos & 255u)] = (unsigned short)key; }
.Lp2_back9:
	ds_read_b128 v[40:43], v118 offset:26624
	ds_read_b128 v[44:47], v119 offset:26624
	s_waitcnt lgkmcnt(2)
	v_mfma_f32_16x16x32_f16 v[48:51], v[0:3], v[32:35], 0
	v_cvt_pkrtz_f16_f32 v75, v70, v71
	v_cvt_pkrtz_f16_f32 v74, v68, v69
	v_pk_max_f16 v75, v75, 0
	v_pk_max_f16 v74, v74, 0
	v_mfma_f32_16x16x32_f16 v[52:55], v[8:11], v[32:35], 0
	v_cvt_pkrtz_f16_f32 v73, v66, v67
	v_cvt_pkrtz_f16_f32 v72, v64, v65
	v_cmp_le_i32_e32 vcc, 160, v93
	v_pk_max_f16 v73, v73, 0
	v_mfma_f32_16x16x32_f16 v[48:51], v[4:7], v[36:39], v[48:51]
	v_pk_max_f16 v72, v72, 0
	v_cmp_le_f32_e64 s[60:61], v95, v76
	v_cmp_le_f32_e64 s[62:63], v94, v76
	v_mfma_f32_16x16x32_f16 v[52:55], v[12:15], v[36:39], v[52:55]
	v_mfma_f32_16x16x32_f16 v[80:83], v[84:87], v[72:75], v[88:91]
	s_and_b64 s[62:63], s[62:63], vcc
	s_and_b64 vcc, vcc, s[60:61]
	v_addc_co_u32_e32 v92, vcc, v92, v92, vcc
	s_andn2_b64 s[62:63], s[62:63], s[60:61]
	s_cbranch_scc1 .Lp2_slow10
.Lp2_back10:
	ds_read_b128 v[32:35], v118 offset:28672
	ds_read_b128 v[36:39], v119 offset:28672
	s_waitcnt lgkmcnt(2)
	v_mfma_f32_16x16x32_f16 v[56:59], v[0:3], v[40:43], 0
	v_cvt_pkrtz_f16_f32 v75, v54, v55
	v_cvt_pkrtz_f16_f32 v74, v52, v53
	v_pk_max_f16 v75, v75, 0
	v_pk_max_f16 v74, v74, 0
	v_mfma_f32_16x16x32_f16 v[60:63], v[8:11], v[40:43], 0
	v_cvt_pkrtz_f16_f32 v73, v50, v51
	v_cvt_pkrtz_f16_f32 v72, v48, v49
	v_cmp_le_i32_e32 vcc, 176, v93
	v_pk_max_f16 v73, v73, 0
	v_mfma_f32_16x16x32_f16 v[56:59], v[4:7], v[44:47], v[56:59]
	v_pk_max_f16 v72, v72, 0
	v_cmp_le_f32_e64 s[60:61], v95, v80
	v_cmp_le_f32_e64 s[62:63], v94, v80
	v_mfma_f32_16x16x32_f16 v[60:63], v[12:15], v[44:47], v[60:63]
	v_mfma_f32_16x16x32_f16 v[76:79], v[84:87], v[72:75], v[88:91]
	s_and_b64 s[62:63], s[62:63], vcc
	s_and_b64 vcc, vcc, s[60:61]
	v_addc_co_u32_e32 v92, vcc, v92, v92, vcc
	s_andn2_b64 s[62:63], s[62:63], s[60:61]
	s_cbranch_scc1 .Lp2_slow11
.Lp2_back11:
	ds_read_b128 v[40:43], v118 offset:30720
	ds_read_b128 v[44:47], v119 offset:30720
	s_waitcnt lgkmcnt(2)
	v_mfma_f32_16x16x32_f16 v[64:67], v[0:3], v[32:35], 0
	v_cvt_pkrtz_f16_f32 v75, v62, v63
	v_cvt_pkrtz_f16_f32 v74, v60, v61
	v_pk_max_f16 v75, v75, 0
	v_pk_max_f16 v74, v74, 0
	v_mfma_f32_16x16x32_f16 v[68:71], v[8:11], v[32:35], 0
	v_cvt_pkrtz_f16_f32 v73, v58, v59
	v_cvt_pkrtz_f16_f32 v72, v56, v57
	v_cmp_le_i32_e32 vcc, 192, v93
	v_pk_max_f16 v73, v73, 0
	v_mfma_f32_16x16x32_f16 v[64:67], v[4:7], v[36:39], v[64:67]
	v_pk_max_f16 v72, v72, 0
	v_cmp_le_f32_e64 s[60:61], v95, v76
	v_cmp_le_f32_e64 s[62:63], v94, v76
	v_mfma_f32_16x16x32_f16 v[68:71], v[12:15], v[36:39], v[68:71]
	v_mfma_f32_16x16x32_f16 v[80:83], v[84:87], v[72:75], v[88:91]
	s_and_b64 s[62:63], s[62:63], vcc
	s_and_b64 vcc, vcc, s[60:61]
	v_addc_co_u32_e32 v92, vcc, v92, v92, vcc
	s_andn2_b64 s[62:63], s[62:63], s[60:61]
	s_cbranch_scc1 .Lp2_slow12
.Lp2_back12:
	s_nop 3
	s_waitcnt lgkmcnt(0)
	v_mfma_f32_16x16x32_f16 v[48:51], v[0:3], v[40:43], 0
	v_cvt_pkrtz_f16_f32 v75, v70, v71
	v_cvt_pkrtz_f16_f32 v74, v68, v69
	v_pk_max_f16 v75, v75, 0
	v_pk_max_f16 v74, v74, 0
	v_mfma_f32_16x16x32_f16 v[52:55], v[8:11], v[40:43], 0
	v_cvt_pkrtz_f16_f32 v73, v66, v67
	v_cvt_pkrtz_f16_f32 v72, v64, v65
	v_cmp_le_i32_e32 vcc, 208, v93
	v_pk_max_f16 v73, v73, 0
	v_mfma_f32_16x16x32_f16 v[48:51], v[4:7], v[44:47], v[48:51]
	v_pk_max_f16 v72, v72, 0
	v_cmp_le_f32_e64 s[60:61], v95, v80
	v_cmp_le_f32_e64 s[62:63], v94, v80
	v_mfma_f32_16x16x32_f16 v[52:55], v[12:15], v[44:47], v[52:55]
	v_mfma_f32_16x16x32_f16 v[76:79], v[84:87], v[72:75], v[88:91]
	s_and_b64 s[62:63], s[62:63], vcc
	s_and_b64 vcc, vcc, s[60:61]
	v_addc_co_u32_e32 v92, vcc, v92, v92, vcc
	s_andn2_b64 s[62:63], s[62:63], s[60:61]
	s_cbranch_scc1 .Lp2_slow13
.Lp2_back13:
	s_nop 3
	v_cvt_pkrtz_f16_f32 v75, v54, v55
	v_cvt_pkrtz_f16_f32 v74, v52, v53
	v_pk_max_f16 v75, v75, 0
	v_pk_max_f16 v74, v74, 0
	v_cvt_pkrtz_f16_f32 v73, v50, v51
	v_cvt_pkrtz_f16_f32 v72, v48, v49
	v_cmp_le_i32_e32 vcc, 224, v93
	v_pk_max_f16 v73, v73, 0
	v_pk_max_f16 v72, v72, 0
	v_cmp_le_f32_e64 s[60:61], v95, v76
	v_cmp_le_f32_e64 s[62:63], v94, v76
	v_mfma_f32_16x16x32_f16 v[80:83], v[84:87], v[72:75], v[88:91]
	s_and_b64 s[62:63], s[62:63], vcc
	s_and_b64 vcc, vcc, s[60:61]
	v_addc_co_u32_e32 v92, vcc, v92, v92, vcc
	s_andn2_b64 s[62:63], s[62:63], s[60:61]
	s_cbranch_scc1 .Lp2_slow14
.Lp2_back14:
	s_nop 7
	s_nop 3
	v_cmp_le_i32_e32 vcc, 240, v93
	v_cmp_le_f32_e64 s[60:61], v95, v80
	v_cmp_le_f32_e64 s[62:63], v94, v80
	s_and_b64 s[62:63], s[62:63], vcc
	s_and_b64 vcc, vcc, s[60:61]
	v_addc_co_u32_e32 v92, vcc, v92, v92, vcc
	s_andn2_b64 s[62:63], s[62:63], s[60:61]
	s_cbranch_scc1 .Lp2_slow15
.Lp2_back15:
.Lp2_wloop:
	v_cmp_ne_u32_e32 vcc, 0, v92
	s_and_b64 exec, exec, vcc
	s_cbranch_execz .Lp2_wdone
	v_ffbh_u32_e32 v200, v92
	ds_add_rtn_u32 v201, v115, v212 offset:8
	v_lshrrev_b32_e32 v202, v200, v123
	v_lshl_add_u32 v200, v200, 4, v122
	v_xor_b32_e32 v92, v92, v202
	s_waitcnt lgkmcnt(0)
	v_and_b32_e32 v201, 0xff, v201
	v_lshl_add_u32 v201, v201, 1, v142
	ds_write_b16 v201, v200
	s_mov_b64 exec, -1
	s_branch .Lp2_wloop
.Lp2_wdone:
	s_mov_b64 exec, -1
	s_branch .Lp2_end
; template <int PASS> ...
;     ...
;                     else if (bin == b0) { const unsigned c = atomicAdd(&myctl[fq * 4 + 3], 1u);
;                         if (c < 128u) { float s = 0.f;
; #pragma unroll
;                             for (int r = 0; r < 4; ++r) s += wv[r] * fmaxf(a0[r], 0.f) + wv[4 + r] * fmaxf(a1[r], 0.f);
;                             s = fminf(fmaxf(s, -3.99f), 3.99f);
;                             mycand[(fq * 128 + c) * 2] = (unsigned)((s + 4.f) * 536870912.f); mycand[(fq * 128 + c) * 2 + 1] = (unsigned)key; } }
.Lp2_slow0:
	s_mov_b64 exec, s[62:63]
	ds_add_rtn_u32 v200, v115, v212 offset:12
	v_max_f32_e32 v201, 0, v52
	v_max_f32_e32 v202, 0, v48
	v_mul_f32_e32 v201, v110, v201
	v_fmac_f32_e32 v201, v106, v202
	v_add_f32_e32 v203, 0, v201
	v_max_f32_e32 v201, 0, v53
	v_max_f32_e32 v202, 0, v49
	v_mul_f32_e32 v201, v111, v201
	v_fmac_f32_e32 v201, v107, v202
	v_add_f32_e32 v203, v201, v203
	v_max_f32_e32 v201, 0, v54
	v_max_f32_e32 v202, 0, v50
	v_mul_f32_e32 v201, v112, v201
	v_fmac_f32_e32 v201, v108, v202
	v_add_f32_e32 v203, v201, v203
	v_max_f32_e32 v201, 0, v55
	v_max_f32_e32 v202, 0, v51
	v_mul_f32_e32 v201, v113, v201
	v_fmac_f32_e32 v201, v109, v202
	v_add_f32_e32 v203, v201, v203
	v_max_f32_e32 v203, 0xc07f5c29, v203
	v_min_f32_e32 v203, 0x407f5c29, v203
	v_add_f32_e32 v203, 4.0, v203
	v_mul_f32_e32 v203, 0x4e000000, v203
	v_cvt_u32_f32_e32 v198, v203
	v_add_u32_e32 v199, 0, v117
	s_waitcnt lgkmcnt(0)
	v_cmp_gt_u32_e32 vcc, s81, v200
	s_and_b64 exec, exec, vcc
	v_lshl_add_u32 v200, v200, 3, v141
	ds_write_b64 v200, v[198:199]
	s_mov_b64 exec, -1
	s_branch .Lp2_back0
.Lp2_slow1:
	s_mov_b64 exec, s[62:63]
	ds_add_rtn_u32 v200, v115, v212 offset:12
	v_max_f32_e32 v201, 0, v60
	v_max_f32_e32 v202, 0, v56
	v_mul_f32_e32 v201, v110, v201
	v_fmac_f32_e32 v201, v106, v202
	v_add_f32_e32 v203, 0, v201
	v_max_f32_e32 v201, 0, v61
	v_max_f32_e32 v202, 0, v57
	v_mul_f32_e32 v201, v111, v201
	v_fmac_f32_e32 v201, v107, v202
	v_add_f32_e32 v203, v201, v203
	v_max_f32_e32 v201, 0, v62
	v_max_f32_e32 v202, 0, v58
	v_mul_f32_e32 v201, v112, v201
	v_fmac_f32_e32 v201, v108, v202
	v_add_f32_e32 v203, v201, v203
	v_max_f32_e32 v201, 0, v63
	v_max_f32_e32 v202, 0, v59
	v_mul_f32_e32 v201, v113, v201
	v_fmac_f32_e32 v201, v109, v202
	v_add_f32_e32 v203, v201, v203
	v_max_f32_e32 v203, 0xc07f5c29, v203
	v_min_f32_e32 v203, 0x407f5c29, v203
	v_add_f32_e32 v203, 4.0, v203
	v_mul_f32_e32 v203, 0x4e000000, v203
	v_cvt_u32_f32_e32 v198, v203
	v_add_u32_e32 v199, 16, v117
	s_waitcnt lgkmcnt(0)
	v_cmp_gt_u32_e32 vcc, s81, v200
	s_and_b64 exec, exec, vcc
	v_lshl_add_u32 v200, v200, 3, v141
	ds_write_b64 v200, v[198:199]
	s_mov_b64 exec, -1
	s_branch .Lp2_back1
.Lp2_slow2:
	s_mov_b64 exec, s[62:63]
	ds_add_rtn_u32 v200, v115, v212 offset:12
	v_max_f32_e32 v201, 0, v68
	v_max_f32_e32 v202, 0, v64
	v_mul_f32_e32 v201, v110, v201
	v_fmac_f32_e32 v201, v106, v202
	v_add_f32_e32 v203, 0, v201
	v_max_f32_e32 v201, 0, v69
	v_max_f32_e32 v202, 0, v65
	v_mul_f32_e32 v201, v111, v201
	v_fmac_f32_e32 v201, v107, v202
	v_add_f32_e32 v203, v201, v203
	v_max_f32_e32 v201, 0, v70
	v_max_f32_e32 v202, 0, v66
	v_mul_f32_e32 v201, v112, v201
	v_fmac_f32_e32 v201, v108, v202
	v_add_f32_e32 v203, v201, v203
	v_max_f32_e32 v201, 0, v71
	v_max_f32_e32 v202, 0, v67
	v_mul_f32_e32 v201, v113, v201
	v_fmac_f32_e32 v201, v109, v202
	v_add_f32_e32 v203, v201, v203
	v_max_f32_e32 v203, 0xc07f5c29, v203
	v_min_f32_e32 v203, 0x407f5c29, v203
	v_add_f32_e32 v203, 4.0, v203
	v_mul_f32_e32 v203, 0x4e000000, v203
	v_cvt_u32_f32_e32 v198, v203
	v_add_u32_e32 v199, 32, v117
	s_waitcnt lgkmcnt(0)
	v_cmp_gt_u32_e32 vcc, s81, v200
	s_and_b64 exec, exec, vcc
	v_lshl_add_u32 v200, v200, 3, v141
	ds_write_b64 v200, v[198:199]
	s_mov_b64 exec, -1
	s_branch .Lp2_back2
.Lp2_slow3:
	s_mov_b64 exec, s[62:63]
	ds_add_rtn_u32 v200, v115, v212 offset:12
	v_max_f32_e32 v201, 0, v52
	v_max_f32_e32 v202, 0, v48
	v_mul_f32_e32 v201, v110, v201
	v_fmac_f32_e32 v201, v106, v202
	v_add_f32_e32 v203, 0, v201
	v_max_f32_e32 v201, 0, v53
	v_max_f32_e32 v202, 0, v49
	v_mul_f32_e32 v201, v111, v201
	v_fmac_f32_e32 v201, v107, v202
	v_add_f32_e32 v203, v201, v203
	v_max_f32_e32 v201, 0, v54
	v_max_f32_e32 v202, 0, v50
	v_mul_f32_e32 v201, v112, v201
	v_fmac_f32_e32 v201, v108, v202
	v_add_f32_e32 v203, v201, v203
	v_max_f32_e32 v201, 0, v55
	v_max_f32_e32 v202, 0, v51
	v_mul_f32_e32 v201, v113, v201
	v_fmac_f32_e32 v201, v109, v202
	v_add_f32_e32 v203, v201, v203
	v_max_f32_e32 v203, 0xc07f5c29, v203
	v_min_f32_e32 v203, 0x407f5c29, v203
	v_add_f32_e32 v203, 4.0, v203
	v_mul_f32_e32 v203, 0x4e000000, v203
	v_cvt_u32_f32_e32 v198, v203
	v_add_u32_e32 v199, 48, v117
	s_waitcnt lgkmcnt(0)
	v_cmp_gt_u32_e32 vcc, s81, v200
	s_and_b64 exec, exec, vcc
	v_lshl_add_u32 v200, v200, 3, v141
	ds_write_b64 v200, v[198:199]
	s_mov_b64 exec, -1
	s_branch .Lp2_back3
.Lp2_slow4:
	s_mov_b64 exec, s[62:63]
	ds_add_rtn_u32 v200, v115, v212 offset:12
	v_max_f32_e32 v201, 0, v60
	v_max_f32_e32 v202, 0, v56
	v_mul_f32_e32 v201, v110, v201
	v_fmac_f32_e32 v201, v106, v202
	v_add_f32_e32 v203, 0, v201
	v_max_f32_e32 v201, 0, v61
	v_max_f32_e32 v202, 0, v57
	v_mul_f32_e32 v201, v111, v201
	v_fmac_f32_e32 v201, v107, v202
	v_add_f32_e32 v203, v201, v203
	v_max_f32_e32 v201, 0, v62
	v_max_f32_e32 v202, 0, v58
	v_mul_f32_e32 v201, v112, v201
	v_fmac_f32_e32 v201, v108, v202
	v_add_f32_e32 v203, v201, v203
	v_max_f32_e32 v201, 0, v63
	v_max_f32_e32 v202, 0, v59
	v_mul_f32_e32 v201, v113, v201
	v_fmac_f32_e32 v201, v109, v202
	v_add_f32_e32 v203, v201, v203
	v_max_f32_e32 v203, 0xc07f5c29, v203
	v_min_f32_e32 v203, 0x407f5c29, v203
	v_add_f32_e32 v203, 4.0, v203
	v_mul_f32_e32 v203, 0x4e000000, v203
	v_cvt_u32_f32_e32 v198, v203
	v_add_u32_e32 v199, 64, v117
	s_waitcnt lgkmcnt(0)
	v_cmp_gt_u32_e32 vcc, s81, v200
	s_and_b64 exec, exec, vcc
	v_lshl_add_u32 v200, v200, 3, v141
	ds_write_b64 v200, v[198:199]
	s_mov_b64 exec, -1
	s_branch .Lp2_back4
; template <int PASS> ...
;     ...
;                     else if (bin == b0) { const unsigned c = atomicAdd(&myctl[fq * 4 + 3], 1u);
;                         if (c < 128u) { float s = 0.f;
; #pragma unroll
;                             for (int r = 0; r < 4; ++r) s += wv[r] * fmaxf(a0[r], 0.f) + wv[4 + r] * fmaxf(a1[r], 0.f);
;                             s = fminf(fmaxf(s, -3.99f), 3.99f);
;                             mycand[(fq * 128 + c) * 2] = (unsigned)((s + 4.f) * 536870912.f); mycand[(fq * 128 + c) * 2 + 1] = (unsigned)key; } }
.Lp2_slow5:
	s_mov_b64 exec, s[62:63]
	ds_add_rtn_u32 v200, v115, v212 offset:12
	v_max_f32_e32 v201, 0, v68
	v_max_f32_e32 v202, 0, v64
	v_mul_f32_e32 v201, v110, v201
	v_fmac_f32_e32 v201, v106, v202
	v_add_f32_e32 v203, 0, v201
	v_max_f32_e32 v201, 0, v69
	v_max_f32_e32 v202, 0, v65
	v_mul_f32_e32 v201, v111, v201
	v_fmac_f32_e32 v201, v107, v202
	v_add_f32_e32 v203, v201, v203
	v_max_f32_e32 v201, 0, v70
	v_max_f32_e32 v202, 0, v66
	v_mul_f32_e32 v201, v112, v201
	v_fmac_f32_e32 v201, v108, v202
	v_add_f32_e32 v203, v201, v203
	v_max_f32_e32 v201, 0, v71
	v_max_f32_e32 v202, 0, v67
	v_mul_f32_e32 v201, v113, v201
	v_fmac_f32_e32 v201, v109, v202
	v_add_f32_e32 v203, v201, v203
	v_max_f32_e32 v203, 0xc07f5c29, v203
	v_min_f32_e32 v203, 0x407f5c29, v203
	v_add_f32_e32 v203, 4.0, v203
	v_mul_f32_e32 v203, 0x4e000000, v203
	v_cvt_u32_f32_e32 v198, v203
	v_add_u32_e32 v199, 80, v117
	s_waitcnt lgkmcnt(0)
	v_cmp_gt_u32_e32 vcc, s81, v200
	s_and_b64 exec, exec, vcc
	v_lshl_add_u32 v200, v200, 3, v141
	ds_write_b64 v200, v[198:199]
	s_mov_b64 exec, -1
	s_branch .Lp2_back5
.Lp2_slow6:
	s_mov_b64 exec, s[62:63]
	ds_add_rtn_u32 v200, v115, v212 offset:12
	v_max_f32_e32 v201, 0, v52
	v_max_f32_e32 v202, 0, v48
	v_mul_f32_e32 v201, v110, v201
	v_fmac_f32_e32 v201, v106, v202
	v_add_f32_e32 v203, 0, v201
	v_max_f32_e32 v201, 0, v53
	v_max_f32_e32 v202, 0, v49
	v_mul_f32_e32 v201, v111, v201
	v_fmac_f32_e32 v201, v107, v202
	v_add_f32_e32 v203, v201, v203
	v_max_f32_e32 v201, 0, v54
	v_max_f32_e32 v202, 0, v50
	v_mul_f32_e32 v201, v112, v201
	v_fmac_f32_e32 v201, v108, v202
	v_add_f32_e32 v203, v201, v203
	v_max_f32_e32 v201, 0, v55
	v_max_f32_e32 v202, 0, v51
	v_mul_f32_e32 v201, v113, v201
	v_fmac_f32_e32 v201, v109, v202
	v_add_f32_e32 v203, v201, v203
	v_max_f32_e32 v203, 0xc07f5c29, v203
	v_min_f32_e32 v203, 0x407f5c29, v203
	v_add_f32_e32 v203, 4.0, v203
	v_mul_f32_e32 v203, 0x4e000000, v203
	v_cvt_u32_f32_e32 v198, v203
	v_add_u32_e32 v199, 96, v117
	s_waitcnt lgkmcnt(0)
	v_cmp_gt_u32_e32 vcc, s81, v200
	s_and_b64 exec, exec, vcc
	v_lshl_add_u32 v200, v200, 3, v141
	ds_write_b64 v200, v[198:199]
	s_mov_b64 exec, -1
	s_branch .Lp2_back6
.Lp2_slow7:
	s_mov_b64 exec, s[62:63]
	ds_add_rtn_u32 v200, v115, v212 offset:12
	v_max_f32_e32 v201, 0, v60
	v_max_f32_e32 v202, 0, v56
	v_mul_f32_e32 v201, v110, v201
	v_fmac_f32_e32 v201, v106, v202
	v_add_f32_e32 v203, 0, v201
	v_max_f32_e32 v201, 0, v61
	v_max_f32_e32 v202, 0, v57
	v_mul_f32_e32 v201, v111, v201
	v_fmac_f32_e32 v201, v107, v202
	v_add_f32_e32 v203, v201, v203
	v_max_f32_e32 v201, 0, v62
	v_max_f32_e32 v202, 0, v58
	v_mul_f32_e32 v201, v112, v201
	v_fmac_f32_e32 v201, v108, v202
	v_add_f32_e32 v203, v201, v203
	v_max_f32_e32 v201, 0, v63
	v_max_f32_e32 v202, 0, v59
	v_mul_f32_e32 v201, v113, v201
	v_fmac_f32_e32 v201, v109, v202
	v_add_f32_e32 v203, v201, v203
	v_max_f32_e32 v203, 0xc07f5c29, v203
	v_min_f32_e32 v203, 0x407f5c29, v203
	v_add_f32_e32 v203, 4.0, v203
	v_mul_f32_e32 v203, 0x4e000000, v203
	v_cvt_u32_f32_e32 v198, v203
	v_add_u32_e32 v199, 112, v117
	s_waitcnt lgkmcnt(0)
	v_cmp_gt_u32_e32 vcc, s81, v200
	s_and_b64 exec, exec, vcc
	v_lshl_add_u32 v200, v200, 3, v141
	ds_write_b64 v200, v[198:199]
	s_mov_b64 exec, -1
	s_branch .Lp2_back7
.Lp2_slow8:
	s_mov_b64 exec, s[62:63]
	ds_add_rtn_u32 v200, v115, v212 offset:12
	v_max_f32_e32 v201, 0, v68
	v_max_f32_e32 v202, 0, v64
	v_mul_f32_e32 v201, v110, v201
	v_fmac_f32_e32 v201, v106, v202
	v_add_f32_e32 v203, 0, v201
	v_max_f32_e32 v201, 0, v69
	v_max_f32_e32 v202, 0, v65
	v_mul_f32_e32 v201, v111, v201
	v_fmac_f32_e32 v201, v107, v202
	v_add_f32_e32 v203, v201, v203
	v_max_f32_e32 v201, 0, v70
	v_max_f32_e32 v202, 0, v66
	v_mul_f32_e32 v201, v112, v201
	v_fmac_f32_e32 v201, v108, v202
	v_add_f32_e32 v203, v201, v203
	v_max_f32_e32 v201, 0, v71
	v_max_f32_e32 v202, 0, v67
	v_mul_f32_e32 v201, v113, v201
	v_fmac_f32_e32 v201, v109, v202
	v_add_f32_e32 v203, v201, v203
	v_max_f32_e32 v203, 0xc07f5c29, v203
	v_min_f32_e32 v203, 0x407f5c29, v203
	v_add_f32_e32 v203, 4.0, v203
	v_mul_f32_e32 v203, 0x4e000000, v203
	v_cvt_u32_f32_e32 v198, v203
	v_add_u32_e32 v199, 128, v117
	s_waitcnt lgkmcnt(0)
	v_cmp_gt_u32_e32 vcc, s81, v200
	s_and_b64 exec, exec, vcc
	v_lshl_add_u32 v200, v200, 3, v141
	ds_write_b64 v200, v[198:199]
	s_mov_b64 exec, -1
	s_branch .Lp2_back8
.Lp2_slow9:
	s_mov_b64 exec, s[62:63]
	ds_add_rtn_u32 v200, v115, v212 offset:12
	v_max_f32_e32 v201, 0, v52
	v_max_f32_e32 v202, 0, v48
	v_mul_f32_e32 v201, v110, v201
	v_fmac_f32_e32 v201, v106, v202
	v_add_f32_e32 v203, 0, v201
	v_max_f32_e32 v201, 0, v53
	v_max_f32_e32 v202, 0, v49
	v_mul_f32_e32 v201, v111, v201
	v_fmac_f32_e32 v201, v107, v202
	v_add_f32_e32 v203, v201, v203
	v_max_f32_e32 v201, 0, v54
	v_max_f32_e32 v202, 0, v50
	v_mul_f32_e32 v201, v112, v201
	v_fmac_f32_e32 v201, v108, v202
	v_add_f32_e32 v203, v201, v203
	v_max_f32_e32 v201, 0, v55
	v_max_f32_e32 v202, 0, v51
	v_mul_f32_e32 v201, v113, v201
	v_fmac_f32_e32 v201, v109, v202
	v_add_f32_e32 v203, v201, v203
	v_max_f32_e32 v203, 0xc07f5c29, v203
	v_min_f32_e32 v203, 0x407f5c29, v203
	v_add_f32_e32 v203, 4.0, v203
	v_mul_f32_e32 v203, 0x4e000000, v203
	v_cvt_u32_f32_e32 v198, v203
	v_add_u32_e32 v199, 144, v117
	s_waitcnt lgkmcnt(0)
	v_cmp_gt_u32_e32 vcc, s81, v200
	s_and_b64 exec, exec, vcc
	v_lshl_add_u32 v200, v200, 3, v141
	ds_write_b64 v200, v[198:199]
	s_mov_b64 exec, -1
	s_branch .Lp2_back9
; template <int PASS> ...
;     ...
;                     else if (bin == b0) { const unsigned c = atomicAdd(&myctl[fq * 4 + 3], 1u);
;                         if (c < 128u) { float s = 0.f;
; #pragma unroll
;                             for (int r = 0; r < 4; ++r) s += wv[r] * fmaxf(a0[r], 0.f) + wv[4 + r] * fmaxf(a1[r], 0.f);
;                             s = fminf(fmaxf(s, -3.99f), 3.99f);
;                             mycand[(fq * 128 + c) * 2] = (unsigned)((s + 4.f) * 536870912.f); mycand[(fq * 128 + c) * 2 + 1] = (unsigned)key; } }
.Lp2_slow10:
	s_mov_b64 exec, s[62:63]
	ds_add_rtn_u32 v200, v115, v212 offset:12
	v_max_f32_e32 v201, 0, v60
	v_max_f32_e32 v202, 0, v56
	v_mul_f32_e32 v201, v110, v201
	v_fmac_f32_e32 v201, v106, v202
	v_add_f32_e32 v203, 0, v201
	v_max_f32_e32 v201, 0, v61
	v_max_f32_e32 v202, 0, v57
	v_mul_f32_e32 v201, v111, v201
	v_fmac_f32_e32 v201, v107, v202
	v_add_f32_e32 v203, v201, v203
	v_max_f32_e32 v201, 0, v62
	v_max_f32_e32 v202, 0, v58
	v_mul_f32_e32 v201, v112, v201
	v_fmac_f32_e32 v201, v108, v202
	v_add_f32_e32 v203, v201, v203
	v_max_f32_e32 v201, 0, v63
	v_max_f32_e32 v202, 0, v59
	v_mul_f32_e32 v201, v113, v201
	v_fmac_f32_e32 v201, v109, v202
	v_add_f32_e32 v203, v201, v203
	v_max_f32_e32 v203, 0xc07f5c29, v203
	v_min_f32_e32 v203, 0x407f5c29, v203
	v_add_f32_e32 v203, 4.0, v203
	v_mul_f32_e32 v203, 0x4e000000, v203
	v_cvt_u32_f32_e32 v198, v203
	v_add_u32_e32 v199, 160, v117
	s_waitcnt lgkmcnt(0)
	v_cmp_gt_u32_e32 vcc, s81, v200
	s_and_b64 exec, exec, vcc
	v_lshl_add_u32 v200, v200, 3, v141
	ds_write_b64 v200, v[198:199]
	s_mov_b64 exec, -1
	s_branch .Lp2_back10
.Lp2_slow11:
	s_mov_b64 exec, s[62:63]
	ds_add_rtn_u32 v200, v115, v212 offset:12
	v_max_f32_e32 v201, 0, v68
	v_max_f32_e32 v202, 0, v64
	v_mul_f32_e32 v201, v110, v201
	v_fmac_f32_e32 v201, v106, v202
	v_add_f32_e32 v203, 0, v201
	v_max_f32_e32 v201, 0, v69
	v_max_f32_e32 v202, 0, v65
	v_mul_f32_e32 v201, v111, v201
	v_fmac_f32_e32 v201, v107, v202
	v_add_f32_e32 v203, v201, v203
	v_max_f32_e32 v201, 0, v70
	v_max_f32_e32 v202, 0, v66
	v_mul_f32_e32 v201, v112, v201
	v_fmac_f32_e32 v201, v108, v202
	v_add_f32_e32 v203, v201, v203
	v_max_f32_e32 v201, 0, v71
	v_max_f32_e32 v202, 0, v67
	v_mul_f32_e32 v201, v113, v201
	v_fmac_f32_e32 v201, v109, v202
	v_add_f32_e32 v203, v201, v203
	v_max_f32_e32 v203, 0xc07f5c29, v203
	v_min_f32_e32 v203, 0x407f5c29, v203
	v_add_f32_e32 v203, 4.0, v203
	v_mul_f32_e32 v203, 0x4e000000, v203
	v_cvt_u32_f32_e32 v198, v203
	v_add_u32_e32 v199, 176, v117
	s_waitcnt lgkmcnt(0)
	v_cmp_gt_u32_e32 vcc, s81, v200
	s_and_b64 exec, exec, vcc
	v_lshl_add_u32 v200, v200, 3, v141
	ds_write_b64 v200, v[198:199]
	s_mov_b64 exec, -1
	s_branch .Lp2_back11
.Lp2_slow12:
	s_mov_b64 exec, s[62:63]
	ds_add_rtn_u32 v200, v115, v212 offset:12
	v_max_f32_e32 v201, 0, v52
	v_max_f32_e32 v202, 0, v48
	v_mul_f32_e32 v201, v110, v201
	v_fmac_f32_e32 v201, v106, v202
	v_add_f32_e32 v203, 0, v201
	v_max_f32_e32 v201, 0, v53
	v_max_f32_e32 v202, 0, v49
	v_mul_f32_e32 v201, v111, v201
	v_fmac_f32_e32 v201, v107, v202
	v_add_f32_e32 v203, v201, v203
	v_max_f32_e32 v201, 0, v54
	v_max_f32_e32 v202, 0, v50
	v_mul_f32_e32 v201, v112, v201
	v_fmac_f32_e32 v201, v108, v202
	v_add_f32_e32 v203, v201, v203
	v_max_f32_e32 v201, 0, v55
	v_max_f32_e32 v202, 0, v51
	v_mul_f32_e32 v201, v113, v201
	v_fmac_f32_e32 v201, v109, v202
	v_add_f32_e32 v203, v201, v203
	v_max_f32_e32 v203, 0xc07f5c29, v203
	v_min_f32_e32 v203, 0x407f5c29, v203
	v_add_f32_e32 v203, 4.0, v203
	v_mul_f32_e32 v203, 0x4e000000, v203
	v_cvt_u32_f32_e32 v198, v203
	v_add_u32_e32 v199, 192, v117
	s_waitcnt lgkmcnt(0)
	v_cmp_gt_u32_e32 vcc, s81, v200
	s_and_b64 exec, exec, vcc
	v_lshl_add_u32 v200, v200, 3, v141
	ds_write_b64 v200, v[198:199]
	s_mov_b64 exec, -1
	s_branch .Lp2_back12
.Lp2_slow13:
	s_mov_b64 exec, s[62:63]
	ds_add_rtn_u32 v200, v115, v212 offset:12
	v_max_f32_e32 v201, 0, v60
	v_max_f32_e32 v202, 0, v56
	v_mul_f32_e32 v201, v110, v201
	v_fmac_f32_e32 v201, v106, v202
	v_add_f32_e32 v203, 0, v201
	v_max_f32_e32 v201, 0, v61
	v_max_f32_e32 v202, 0, v57
	v_mul_f32_e32 v201, v111, v201
	v_fmac_f32_e32 v201, v107, v202
	v_add_f32_e32 v203, v201, v203
	v_max_f32_e32 v201, 0, v62
	v_max_f32_e32 v202, 0, v58
	v_mul_f32_e32 v201, v112, v201
	v_fmac_f32_e32 v201, v108, v202
	v_add_f32_e32 v203, v201, v203
	v_max_f32_e32 v201, 0, v63
	v_max_f32_e32 v202, 0, v59
	v_mul_f32_e32 v201, v113, v201
	v_fmac_f32_e32 v201, v109, v202
	v_add_f32_e32 v203, v201, v203
	v_max_f32_e32 v203, 0xc07f5c29, v203
	v_min_f32_e32 v203, 0x407f5c29, v203
	v_add_f32_e32 v203, 4.0, v203
	v_mul_f32_e32 v203, 0x4e000000, v203
	v_cvt_u32_f32_e32 v198, v203
	v_add_u32_e32 v199, 208, v117
	s_waitcnt lgkmcnt(0)
	v_cmp_gt_u32_e32 vcc, s81, v200
	s_and_b64 exec, exec, vcc
	v_lshl_add_u32 v200, v200, 3, v141
	ds_write_b64 v200, v[198:199]
	s_mov_b64 exec, -1
	s_branch .Lp2_back13
.Lp2_slow14:
	s_mov_b64 exec, s[62:63]
	ds_add_rtn_u32 v200, v115, v212 offset:12
	v_max_f32_e32 v201, 0, v68
	v_max_f32_e32 v202, 0, v64
	v_mul_f32_e32 v201, v110, v201
	v_fmac_f32_e32 v201, v106, v202
	v_add_f32_e32 v203, 0, v201
	v_max_f32_e32 v201, 0, v69
	v_max_f32_e32 v202, 0, v65
	v_mul_f32_e32 v201, v111, v201
	v_fmac_f32_e32 v201, v107, v202
	v_add_f32_e32 v203, v201, v203
	v_max_f32_e32 v201, 0, v70
	v_max_f32_e32 v202, 0, v66
	v_mul_f32_e32 v201, v112, v201
	v_fmac_f32_e32 v201, v108, v202
	v_add_f32_e32 v203, v201, v203
	v_max_f32_e32 v201, 0, v71
	v_max_f32_e32 v202, 0, v67
	v_mul_f32_e32 v201, v113, v201
	v_fmac_f32_e32 v201, v109, v202
	v_add_f32_e32 v203, v201, v203
	v_max_f32_e32 v203, 0xc07f5c29, v203
	v_min_f32_e32 v203, 0x407f5c29, v203
	v_add_f32_e32 v203, 4.0, v203
	v_mul_f32_e32 v203, 0x4e000000, v203
	v_cvt_u32_f32_e32 v198, v203
	v_add_u32_e32 v199, 224, v117
	s_waitcnt lgkmcnt(0)
	v_cmp_gt_u32_e32 vcc, s81, v200
	s_and_b64 exec, exec, vcc
	v_lshl_add_u32 v200, v200, 3, v141
	ds_write_b64 v200, v[198:199]
	s_mov_b64 exec, -1
	s_branch .Lp2_back14
.Lp2_slow15:
	s_mov_b64 exec, s[62:63]
	ds_add_rtn_u32 v200, v115, v212 offset:12
	v_max_f32_e32 v201, 0, v52
	v_max_f32_e32 v202, 0, v48
	v_mul_f32_e32 v201, v110, v201
	v_fmac_f32_e32 v201, v106, v202
	v_add_f32_e32 v203, 0, v201
	v_max_f32_e32 v201, 0, v53
	v_max_f32_e32 v202, 0, v49
	v_mul_f32_e32 v201, v111, v201
	v_fmac_f32_e32 v201, v107, v202
	v_add_f32_e32 v203, v201, v203
	v_max_f32_e32 v201, 0, v54
	v_max_f32_e32 v202, 0, v50
	v_mul_f32_e32 v201, v112, v201
	v_fmac_f32_e32 v201, v108, v202
	v_add_f32_e32 v203, v201, v203
	v_max_f32_e32 v201, 0, v55
	v_max_f32_e32 v202, 0, v51
	v_mul_f32_e32 v201, v113, v201
	v_fmac_f32_e32 v201, v109, v202
	v_add_f32_e32 v203, v201, v203
	v_max_f32_e32 v203, 0xc07f5c29, v203
	v_min_f32_e32 v203, 0x407f5c29, v203
	v_add_f32_e32 v203, 4.0, v203
	v_mul_f32_e32 v203, 0x4e000000, v203
	v_cvt_u32_f32_e32 v198, v203
	v_add_u32_e32 v199, 240, v117
	s_waitcnt lgkmcnt(0)
	v_cmp_gt_u32_e32 vcc, s81, v200
	s_and_b64 exec, exec, vcc
	v_lshl_add_u32 v200, v200, 3, v141
	ds_write_b64 v200, v[198:199]
	s_mov_b64 exec, -1
	s_branch .Lp2_back15
.Lp2_end:
	s_andn2_b64 vcc, exec, s[58:59]
	s_mov_b64 s[58:59], -1
	s_cbranch_vccnz .LBB0_423
	s_add_i32 s4, s85, 0x8000
	s_mov_b64 s[58:59], 0
